# v3 plus: in every GEMM prologue the polling wave issues its first weight stage loads after ClusterFinish (other waves before), so the poll does not wait behind cold weight loads
# baseline (speedup 1.0000x reference)
.LBB0_99:
	s_and_b64 vcc, exec, s[6:7]
	s_cbranch_vccz .LBB0_132
	v_ashrrev_i32_e32 v3, 31, v2
	v_lshrrev_b32_e32 v3, 26, v3
	v_add_u32_e32 v3, v2, v3
	v_ashrrev_i32_e32 v4, 6, v3
	v_bfe_i32 v3, v2, 27, 1
	v_lshlrev_b32_e32 v5, 4, v2
	v_lshrrev_b32_e32 v3, 22, v3
	v_add_u32_e32 v3, v5, v3
	v_and_b32_e32 v3, 0xfffffc00, v3
	v_sub_u32_e32 v3, v5, v3
	v_lshrrev_b32_e32 v6, 4, v3
	v_bitop3_b32 v6, v6, v3, 32 bitop3:0x6c
	v_ashrrev_i32_e32 v7, 31, v6
	v_lshrrev_b32_e32 v7, 26, v7
	v_add_u32_e32 v7, v6, v7
	v_ashrrev_i32_e32 v8, 6, v7
	v_and_b32_e32 v7, 0xc0, v7
	v_sub_u32_e32 v6, v6, v7
	v_mov_b32_e32 v7, 1
	v_lshlrev_b32_e32 v3, 3, v4
	v_lshlrev_b32_e32 v4, 5, v4
	v_ashrrev_i16_sdwa v6, v7, sext(v6) dst_sel:DWORD dst_unused:UNUSED_PAD src0_sel:DWORD src1_sel:BYTE_0
	v_and_b32_e32 v3, -16, v3
	v_and_b32_e32 v4, 32, v4
	v_bfe_i32 v6, v6, 0, 16
	v_add_u32_e32 v5, 0x2000, v5
	v_add_u32_e32 v3, v8, v3
	v_add_lshl_u32 v4, v4, v6, 1
	v_ashrrev_i32_e32 v6, 31, v5
	v_lshlrev_b32_e32 v9, 1, v3
	v_lshrrev_b32_e32 v10, 2, v3
	v_and_b32_e32 v8, 3, v8
	s_mov_b32 s7, 0x1fffe0
	v_lshrrev_b32_e32 v6, 22, v6
	v_and_b32_e32 v9, 24, v9
	v_and_b32_e32 v10, 4, v10
	v_and_or_b32 v8, v3, s7, v8
	v_add_u32_e32 v6, v5, v6
	v_or3_b32 v8, v8, v10, v9
	v_ashrrev_i32_e32 v6, 10, v6
	v_lshl_add_u32 v154, v8, 11, v4
	v_mul_i32_i24_e32 v8, 0x400, v6
	v_sub_u32_e32 v5, v5, v8
	v_lshrrev_b32_e32 v8, 4, v5
	v_bitop3_b32 v8, v8, v5, 32 bitop3:0x6c
	v_ashrrev_i32_e32 v9, 31, v8
	v_lshrrev_b32_e32 v9, 26, v9
	v_lshlrev_b32_e32 v5, 3, v6
	v_add_u32_e32 v9, v8, v9
	s_add_u32 s8, s2, 0x200000
	v_and_b32_e32 v5, -16, v5
	v_ashrrev_i32_e32 v10, 6, v9
	s_addc_u32 s6, s3, 0
	v_add_u32_e32 v5, v10, v5
	v_and_b32_e32 v10, 3, v10
	s_ashr_i32 s20, s18, 31
	v_and_or_b32 v10, v5, s7, v10
	s_lshr_b32 s7, s20, 29
	s_add_i32 s7, s18, s7
	s_ashr_i32 s34, s41, 6
	s_ashr_i32 s12, s7, 3
	s_and_b32 s7, s7, -8
	s_and_b32 s9, s6, 0xffff
	s_lshl_b32 s6, s34, 10
	s_sub_i32 s7, s18, s7
	s_cmp_lt_i32 s7, 0
	s_movk_i32 s13, 0x61
	s_cselect_b32 s13, s13, 0x60
	s_mul_i32 s7, s7, s13
	s_add_i32 s7, s7, s12
	s_mul_hi_i32 s12, s7, 0x2aaaaaab
	s_lshr_b32 s13, s12, 31
	s_ashr_i32 s26, s12, 4
	s_add_i32 s26, s26, s13
	s_mul_i32 s12, s26, 0x60
	s_sub_i32 s27, s7, s12
	s_bfe_i32 s7, s27, 0x80000
	s_bfe_u32 s7, s7, 0x3000c
	v_and_b32_e32 v9, 0xc0, v9
	s_add_i32 s7, s27, s7
	v_sub_u32_e32 v8, v8, v9
	s_bfe_i32 s7, s7, 0x80000
	v_lshlrev_b32_e32 v6, 5, v6
	v_ashrrev_i16_sdwa v7, v7, sext(v8) dst_sel:DWORD dst_unused:UNUSED_PAD src0_sel:DWORD src1_sel:BYTE_0
	v_lshlrev_b32_e32 v8, 1, v5
	v_lshrrev_b32_e32 v9, 2, v5
	s_sext_i32_i16 s28, s7
	v_and_b32_e32 v6, 32, v6
	v_bfe_i32 v7, v7, 0, 16
	v_and_b32_e32 v8, 24, v8
	v_and_b32_e32 v9, 4, v9
	s_ashr_i32 s46, s28, 3
	s_add_i32 s21, s6, 0
	v_or3_b32 v8, v10, v9, v8
	v_add_lshl_u32 v6, v6, v7, 1
	s_mov_b32 s11, 0x20000
	s_mov_b32 s10, -1
	s_lshl_b32 s53, s46, 19
	s_add_i32 s22, s21, 0x10000
	v_lshl_add_u32 v155, v8, 11, v6
	s_add_i32 s23, s21, 0x12000
	s_add_i32 s24, s21, 0x14000
	s_or_b32 s6, s53, 0x40000
	s_add_i32 s25, s21, 0x16000
	v_cmp_eq_u32_e32 vcc, 0, v0
	s_nop 3
	s_cmp_lg_u64 vcc, 0
	s_cbranch_scc1 .Lw0s_GEMM1
	s_mov_b32 m0, s22
	s_nop 0
	buffer_load_dwordx4 v154, s[8:11], s53 offen lds
	s_nop 0
	s_mov_b32 m0, s23
	s_nop 0
	buffer_load_dwordx4 v155, s[8:11], s53 offen lds
	s_nop 0
	s_mov_b32 m0, s24
	s_nop 0
	buffer_load_dwordx4 v154, s[8:11], s6 offen lds
	s_nop 0
	s_mov_b32 m0, s25
	s_nop 0
	buffer_load_dwordx4 v155, s[8:11], s6 offen lds
	s_nop 0
.Lw0s_GEMM1:
	s_and_saveexec_b64 s[6:7], vcc
	s_cbranch_execz .LBB0_113
	v_mov_b32_e32 v7, 0
	global_load_dword v8, v7, s[4:5] sc1
	s_waitcnt vmcnt(0)
	v_cmp_lt_u32_e32 vcc, 3, v8
	s_cbranch_vccnz .LBB0_112
	s_mov_b32 s29, 1
	s_branch .LBB0_104

.LBB0_113:
	s_or_b64 exec, exec, s[6:7]
	s_lshr_b32 s0, s28, 3
	s_lshl_b32 s0, s0, 3
	s_sub_i32 s0, s27, s0
	s_lshl_b32 s1, s26, 3
	s_sext_i32_i8 s0, s0
	s_add_i32 s51, s1, s0
	s_lshl_b32 s52, s51, 19
	s_add_u32 s12, s2, 0x3000000
	s_addc_u32 s0, s3, 0
	v_lshl_add_u32 v156, v3, 11, v4
	s_and_b32 s13, s0, 0xffff
	s_mov_b32 s15, 0x20000
	s_mov_b32 s14, -1
	s_barrier
	v_cmp_eq_u32_e32 vcc, 0, v0
	s_nop 3
	s_cmp_eq_u64 vcc, 0
	s_cbranch_scc1 .Lw0n_GEMM1
	s_or_b32 s32, s53, 0x40000
	s_mov_b32 m0, s22
	s_nop 0
	buffer_load_dwordx4 v154, s[8:11], s53 offen lds
	s_nop 0
	s_mov_b32 m0, s23
	s_nop 0
	buffer_load_dwordx4 v155, s[8:11], s53 offen lds
	s_nop 0
	s_mov_b32 m0, s24
	s_nop 0
	buffer_load_dwordx4 v154, s[8:11], s32 offen lds
	s_nop 0
	s_mov_b32 m0, s25
	s_nop 0
	buffer_load_dwordx4 v155, s[8:11], s32 offen lds
	s_nop 0
.Lw0n_GEMM1:
	s_mov_b32 m0, s21
	s_nop 0
	buffer_load_dwordx4 v156, s[12:15], s52 offen lds
	v_lshl_add_u32 v157, v5, 11, v6
	s_add_i32 s27, s21, 0x2000
	s_mov_b32 m0, s27
	s_nop 0
	buffer_load_dwordx4 v157, s[12:15], s52 offen lds
	s_add_i32 s28, s21, 0x4000
	s_or_b32 s5, s52, 0x40000
	s_mov_b32 m0, s28
	s_nop 0
	buffer_load_dwordx4 v156, s[12:15], s5 offen lds
	s_ashr_i32 s4, s41, 8
	s_add_i32 s30, s21, 0x6000
	s_mov_b32 m0, s30
	s_nop 0
	buffer_load_dwordx4 v157, s[12:15], s5 offen lds
	s_cmp_eq_u32 s4, 1
	s_mov_b32 s26, 0
	s_mov_b32 s29, 0x40000
	s_cselect_b64 s[0:1], -1, 0
	s_cmp_lg_u32 s4, 1
	s_cbranch_scc1 .LBB0_115
	s_barrier

.LBB0_199:
	v_bfe_i32 v4, v210, 27, 1
	v_lshlrev_b32_e32 v2, 4, v210
	v_lshrrev_b32_e32 v4, 22, v4
	v_add_u32_e32 v4, v2, v4
	v_and_b32_e32 v4, 0xfffffc00, v4
	v_sub_u32_e32 v4, v2, v4
	v_lshrrev_b32_e32 v5, 4, v4
	v_bitop3_b32 v4, v5, v4, 32 bitop3:0x6c
	v_ashrrev_i32_e32 v3, 31, v210
	v_ashrrev_i32_e32 v6, 31, v4
	v_lshrrev_b32_e32 v3, 26, v3
	v_lshrrev_b32_e32 v6, 26, v6
	v_add_u32_e32 v3, v210, v3
	v_add_u32_e32 v6, v4, v6
	v_ashrrev_i32_e32 v3, 6, v3
	v_lshrrev_b32_e32 v7, 6, v6
	v_and_b32_e32 v6, 0xc0, v6
	v_lshlrev_b32_e32 v5, 3, v3
	v_lshlrev_b32_e32 v3, 5, v3
	v_sub_u32_e32 v4, v4, v6
	v_mov_b32_e32 v6, 1
	v_and_b32_e32 v5, 0x1ffff0, v5
	v_and_b32_e32 v3, 32, v3
	v_ashrrev_i16_sdwa v4, v6, sext(v4) dst_sel:DWORD dst_unused:UNUSED_PAD src0_sel:DWORD src1_sel:BYTE_0
	v_add_u32_sdwa v3, v3, sext(v4) dst_sel:DWORD dst_unused:UNUSED_PAD src0_sel:DWORD src1_sel:WORD_0
	v_add_lshl_u32 v4, v7, v5, 11
	v_add_u32_e32 v2, 0x2000, v2
	v_lshl_add_u32 v130, v3, 1, v4
	v_ashrrev_i32_e32 v3, 31, v2
	s_add_u32 s8, s16, 0x800000
	v_lshrrev_b32_e32 v3, 22, v3
	s_addc_u32 s5, s17, 0
	v_add_u32_e32 v3, v2, v3
	s_add_i32 s4, s6, s4
	v_ashrrev_i32_e32 v3, 10, v3
	s_ashr_i32 s6, s4, 31
	v_mul_i32_i24_e32 v4, 0x400, v3
	s_lshr_b32 s6, s6, 27
	v_sub_u32_e32 v2, v2, v4
	s_add_i32 s28, s4, s6
	v_lshrrev_b32_e32 v4, 4, v2
	s_and_b32 s6, s28, 0xffe0
	v_bitop3_b32 v2, v4, v2, 32 bitop3:0x6c
	s_sub_i32 s24, s4, s6
	v_ashrrev_i32_e32 v5, 31, v2
	s_bfe_i32 s4, s24, 0x80000
	v_lshrrev_b32_e32 v5, 26, v5
	s_bfe_u32 s4, s4, 0x3000c
	v_add_u32_e32 v5, v2, v5
	s_add_i32 s4, s24, s4
	s_ashr_i32 s19, s27, 6
	v_lshrrev_b32_e32 v7, 6, v5
	v_and_b32_e32 v5, 0xc0, v5
	s_bfe_i32 s4, s4, 0x80000
	v_lshlrev_b32_e32 v4, 3, v3
	v_lshlrev_b32_e32 v3, 5, v3
	v_sub_u32_e32 v2, v2, v5
	s_and_b32 s9, s5, 0xffff
	s_lshl_b32 s5, s19, 10
	s_sext_i32_i16 s29, s4
	v_and_b32_e32 v4, 0x1ffff0, v4
	v_and_b32_e32 v3, 32, v3
	v_ashrrev_i16_sdwa v2, v6, sext(v2) dst_sel:DWORD dst_unused:UNUSED_PAD src0_sel:DWORD src1_sel:BYTE_0
	s_ashr_i32 s18, s29, 3
	s_add_i32 s31, s5, 0
	v_add_u32_sdwa v2, v3, sext(v2) dst_sel:DWORD dst_unused:UNUSED_PAD src0_sel:DWORD src1_sel:WORD_0
	v_add_lshl_u32 v3, v7, v4, 11
	s_mov_b32 s11, 0x20000
	s_mov_b32 s10, -1
	s_lshl_b32 s34, s18, 19
	s_add_i32 s33, s31, 0x10000
	v_lshl_add_u32 v131, v2, 1, v3
	s_add_i32 s35, s31, 0x12000
	s_add_i32 s36, s31, 0x14000
	s_or_b32 s4, s34, 0x40000
	s_add_i32 s37, s31, 0x16000
	s_cmp_lg_u64 s[56:57], 0
	s_cbranch_scc1 .Lw0s_GEMM3
	s_mov_b32 m0, s33
	s_nop 0
	buffer_load_dwordx4 v130, s[8:11], s34 offen lds
	s_nop 0
	s_mov_b32 m0, s35
	s_nop 0
	buffer_load_dwordx4 v131, s[8:11], s34 offen lds
	s_nop 0
	s_mov_b32 m0, s36
	s_nop 0
	buffer_load_dwordx4 v130, s[8:11], s4 offen lds
	s_nop 0
	s_mov_b32 m0, s37
	s_nop 0
	buffer_load_dwordx4 v131, s[8:11], s4 offen lds
	s_nop 0
.Lw0s_GEMM3:
	s_and_saveexec_b64 s[4:5], s[56:57]
	s_cbranch_execz .LBB0_212
	v_mov_b32_e32 v2, 0
	global_load_dword v3, v2, s[2:3] sc1
	s_waitcnt vmcnt(0)
	v_cmp_lt_u32_e32 vcc, 11, v3
	s_cbranch_vccnz .LBB0_211
	s_mov_b32 s38, 1
	s_branch .LBB0_203

.LBB0_212:
	s_or_b64 exec, exec, s[4:5]
	s_lshr_b32 s3, s29, 3
	s_lshl_b32 s3, s3, 3
	s_ashr_i32 s2, s28, 5
	s_sub_i32 s3, s24, s3
	s_lshl_b32 s2, s2, 3
	s_sext_i32_i8 s3, s3
	s_add_i32 s29, s2, s3
	s_lshl_b32 s39, s29, 19
	s_add_u32 s12, s16, 0xa800000
	s_addc_u32 s2, s17, 0
	s_and_b32 s13, s2, 0xffff
	s_mov_b32 s15, 0x20000
	s_mov_b32 s14, -1
	s_barrier
	s_cmp_eq_u64 s[56:57], 0
	s_cbranch_scc1 .Lw0n_GEMM3
	s_or_b32 s32, s34, 0x40000
	s_mov_b32 m0, s33
	s_nop 0
	buffer_load_dwordx4 v130, s[8:11], s34 offen lds
	s_nop 0
	s_mov_b32 m0, s35
	s_nop 0
	buffer_load_dwordx4 v131, s[8:11], s34 offen lds
	s_nop 0
	s_mov_b32 m0, s36
	s_nop 0
	buffer_load_dwordx4 v130, s[8:11], s32 offen lds
	s_nop 0
	s_mov_b32 m0, s37
	s_nop 0
	buffer_load_dwordx4 v131, s[8:11], s32 offen lds
	s_nop 0
.Lw0n_GEMM3:
	s_mov_b32 m0, s31
	s_nop 0
	buffer_load_dwordx4 v130, s[12:15], s39 offen lds
	s_add_i32 s40, s31, 0x2000
	s_mov_b32 m0, s40
	s_nop 0
	buffer_load_dwordx4 v131, s[12:15], s39 offen lds
	s_add_i32 s41, s31, 0x4000
	s_or_b32 s2, s39, 0x40000
	s_mov_b32 m0, s41
	s_nop 0
	buffer_load_dwordx4 v130, s[12:15], s2 offen lds
	s_add_i32 s42, s31, 0x6000
	s_mov_b32 m0, s42
	s_nop 0
	buffer_load_dwordx4 v131, s[12:15], s2 offen lds
	s_ashr_i32 s24, s27, 8
	s_cmp_lg_u32 s24, 1
	s_cbranch_scc1 .LBB0_214
	s_barrier

.LBB0_326:
	s_and_b64 vcc, exec, s[4:5]
	s_cbranch_vccz .LBB0_341
	v_ashrrev_i32_e32 v3, 31, v2
	v_lshrrev_b32_e32 v3, 26, v3
	v_add_u32_e32 v3, v2, v3
	v_ashrrev_i32_e32 v4, 6, v3
	v_bfe_i32 v3, v2, 27, 1
	v_lshlrev_b32_e32 v5, 4, v2
	v_lshrrev_b32_e32 v3, 22, v3
	v_add_u32_e32 v3, v5, v3
	v_and_b32_e32 v3, 0xfffffc00, v3
	v_sub_u32_e32 v3, v5, v3
	v_lshrrev_b32_e32 v6, 4, v3
	v_bitop3_b32 v6, v6, v3, 32 bitop3:0x6c
	v_ashrrev_i32_e32 v7, 31, v6
	v_lshrrev_b32_e32 v7, 26, v7
	v_add_u32_e32 v7, v6, v7
	v_ashrrev_i32_e32 v8, 6, v7
	v_and_b32_e32 v7, 0xc0, v7
	v_sub_u32_e32 v6, v6, v7
	v_mov_b32_e32 v7, 1
	v_lshlrev_b32_e32 v3, 3, v4
	v_lshlrev_b32_e32 v4, 5, v4
	v_ashrrev_i16_sdwa v6, v7, sext(v6) dst_sel:DWORD dst_unused:UNUSED_PAD src0_sel:DWORD src1_sel:BYTE_0
	v_and_b32_e32 v3, -16, v3
	v_and_b32_e32 v4, 32, v4
	v_bfe_i32 v6, v6, 0, 16
	v_add_u32_e32 v5, 0x2000, v5
	v_add_u32_e32 v3, v8, v3
	v_add_lshl_u32 v4, v4, v6, 1
	v_ashrrev_i32_e32 v6, 31, v5
	v_lshlrev_b32_e32 v9, 1, v3
	v_lshrrev_b32_e32 v10, 2, v3
	v_and_b32_e32 v8, 3, v8
	s_mov_b32 s5, 0x3fffe0
	v_lshrrev_b32_e32 v6, 22, v6
	v_and_b32_e32 v9, 24, v9
	v_and_b32_e32 v10, 4, v10
	v_and_or_b32 v8, v3, s5, v8
	v_add_u32_e32 v6, v5, v6
	v_or3_b32 v8, v8, v10, v9
	v_ashrrev_i32_e32 v6, 10, v6
	v_lshl_add_u32 v145, v8, 10, v4
	v_mul_i32_i24_e32 v8, 0x400, v6
	v_sub_u32_e32 v5, v5, v8
	v_lshrrev_b32_e32 v8, 4, v5
	v_bitop3_b32 v8, v8, v5, 32 bitop3:0x6c
	v_ashrrev_i32_e32 v9, 31, v8
	v_lshrrev_b32_e32 v9, 26, v9
	v_lshlrev_b32_e32 v5, 3, v6
	v_add_u32_e32 v9, v8, v9
	s_add_u32 s8, s16, 0xa00000
	v_and_b32_e32 v5, -16, v5
	v_ashrrev_i32_e32 v10, 6, v9
	s_addc_u32 s4, s17, 0
	v_add_u32_e32 v5, v10, v5
	v_and_b32_e32 v10, 3, v10
	s_ashr_i32 s31, s28, 31
	v_and_or_b32 v10, v5, s5, v10
	s_lshr_b32 s5, s31, 29
	s_add_i32 s5, s28, s5
	s_ashr_i32 s25, s24, 6
	s_ashr_i32 s6, s5, 3
	s_and_b32 s5, s5, -8
	s_and_b32 s9, s4, 0xffff
	s_lshl_b32 s4, s25, 10
	s_sub_i32 s5, s28, s5
	s_cmp_lt_i32 s5, 0
	s_movk_i32 s7, 0xb1
	s_cselect_b32 s7, s7, 0xb0
	s_mul_i32 s5, s5, s7
	s_add_i32 s5, s5, s6
	s_mul_hi_i32 s6, s5, 0x2e8ba2e9
	s_lshr_b32 s7, s6, 31
	s_ashr_i32 s20, s6, 5
	s_add_i32 s20, s20, s7
	s_mul_i32 s6, s20, 0xb0
	s_sub_i32 s21, s5, s6
	v_and_b32_e32 v9, 0xc0, v9
	s_bfe_u32 s5, s21, 0x3001c
	v_sub_u32_e32 v8, v8, v9
	s_add_i32 s5, s21, s5
	v_lshlrev_b32_e32 v6, 5, v6
	v_ashrrev_i16_sdwa v7, v7, sext(v8) dst_sel:DWORD dst_unused:UNUSED_PAD src0_sel:DWORD src1_sel:BYTE_0
	v_lshlrev_b32_e32 v8, 1, v5
	v_lshrrev_b32_e32 v9, 2, v5
	s_sext_i32_i16 s22, s5
	v_and_b32_e32 v6, 32, v6
	v_bfe_i32 v7, v7, 0, 16
	v_and_b32_e32 v8, 24, v8
	v_and_b32_e32 v9, 4, v9
	s_ashr_i32 s60, s22, 3
	s_add_i32 s33, s4, 0
	v_or3_b32 v8, v10, v9, v8
	v_add_lshl_u32 v6, v6, v7, 1
	s_mov_b32 s11, 0x20000
	s_mov_b32 s10, -1
	s_lshl_b32 s64, s60, 18
	s_add_i32 s34, s33, 0x10000
	v_lshl_add_u32 v146, v8, 10, v6
	s_add_i32 s35, s33, 0x12000
	s_add_i32 s36, s33, 0x14000
	s_or_b32 s4, s64, 0x20000
	s_add_i32 s37, s33, 0x16000
	s_cmp_lg_u64 s[56:57], 0
	s_cbranch_scc1 .Lw0s_GEMM5
	s_mov_b32 m0, s34
	s_nop 0
	buffer_load_dwordx4 v145, s[8:11], s64 offen lds
	s_nop 0
	s_mov_b32 m0, s35
	s_nop 0
	buffer_load_dwordx4 v146, s[8:11], s64 offen lds
	s_nop 0
	s_mov_b32 m0, s36
	s_nop 0
	buffer_load_dwordx4 v145, s[8:11], s4 offen lds
	s_nop 0
	s_mov_b32 m0, s37
	s_nop 0
	buffer_load_dwordx4 v146, s[8:11], s4 offen lds
	s_nop 0
.Lw0s_GEMM5:
	s_and_saveexec_b64 s[4:5], s[56:57]
	s_cbranch_execz .LBB0_345
	v_mov_b32_e32 v7, 0
	global_load_dword v8, v7, s[2:3] sc1
	s_waitcnt vmcnt(0)
	v_cmp_lt_u32_e32 vcc, 19, v8
	s_cbranch_vccnz .LBB0_344
	s_mov_b32 s23, 1
	s_branch .LBB0_331

.LBB0_345:
	s_or_b64 exec, exec, s[4:5]
	s_lshr_b32 s0, s22, 3
	s_lshl_b32 s0, s0, 3
	s_sub_i32 s0, s21, s0
	s_lshl_b32 s1, s20, 3
	s_sext_i32_i16 s0, s0
	s_add_i32 s61, s1, s0
	s_lshl_b32 s63, s61, 19
	s_add_u32 s12, s16, 0xa800000
	s_addc_u32 s1, s17, 0
	v_lshl_add_u32 v147, v3, 10, v4
	s_and_b32 s13, s1, 0xffff
	s_mov_b32 s15, 0x20000
	s_mov_b32 s14, -1
	s_barrier
	s_cmp_eq_u64 s[56:57], 0
	s_cbranch_scc1 .Lw0n_GEMM5
	s_or_b32 s32, s64, 0x20000
	s_mov_b32 m0, s34
	s_nop 0
	buffer_load_dwordx4 v145, s[8:11], s64 offen lds
	s_nop 0
	s_mov_b32 m0, s35
	s_nop 0
	buffer_load_dwordx4 v146, s[8:11], s64 offen lds
	s_nop 0
	s_mov_b32 m0, s36
	s_nop 0
	buffer_load_dwordx4 v145, s[8:11], s32 offen lds
	s_nop 0
	s_mov_b32 m0, s37
	s_nop 0
	buffer_load_dwordx4 v146, s[8:11], s32 offen lds
	s_nop 0
.Lw0n_GEMM5:
	s_mov_b32 m0, s33
	s_nop 0
	buffer_load_dwordx4 v147, s[12:15], s63 offen lds
	v_lshl_add_u32 v148, v5, 10, v6
	s_add_i32 s2, s33, 0x2000
	s_mov_b32 m0, s2
	s_nop 0
	buffer_load_dwordx4 v148, s[12:15], s63 offen lds
	s_add_i32 s3, s33, 0x4000
	s_or_b32 s1, s63, 0x20000
	s_mov_b32 m0, s3
	s_nop 0
	buffer_load_dwordx4 v147, s[12:15], s1 offen lds
	s_ashr_i32 s0, s24, 8
	s_add_i32 s38, s33, 0x6000
	s_mov_b32 m0, s38
	s_nop 0
	buffer_load_dwordx4 v148, s[12:15], s1 offen lds
	s_cmp_eq_u32 s0, 1
	s_mov_b32 s58, 0
	s_cselect_b64 s[6:7], -1, 0
	s_cmp_lg_u32 s0, 1
	s_cbranch_scc1 .LBB0_347
	s_barrier

.LBB0_438:
	s_and_b64 vcc, exec, s[2:3]
	s_cbranch_vccz .LBB0_525
	v_bfe_i32 v4, v146, 27, 1
	v_lshlrev_b32_e32 v2, 4, v146
	v_lshrrev_b32_e32 v4, 22, v4
	v_add_u32_e32 v4, v2, v4
	v_and_b32_e32 v4, 0xfffffc00, v4
	v_sub_u32_e32 v4, v2, v4
	v_ashrrev_i32_e32 v3, 31, v146
	v_lshrrev_b32_e32 v5, 4, v4
	v_lshrrev_b32_e32 v3, 26, v3
	v_bitop3_b32 v4, v5, v4, 32 bitop3:0x6c
	v_add_u32_e32 v3, v146, v3
	v_ashrrev_i32_e32 v6, 31, v4
	v_ashrrev_i32_e32 v3, 6, v3
	v_lshrrev_b32_e32 v6, 26, v6
	v_lshlrev_b32_e32 v5, 3, v3
	v_add_u32_e32 v6, v4, v6
	v_and_b32_e32 v5, 0xfffff0, v5
	v_lshrrev_b32_e32 v7, 6, v6
	v_and_b32_e32 v6, 0xc0, v6
	v_add_u32_e32 v5, v7, v5
	v_sub_u32_e32 v4, v4, v6
	v_mov_b32_e32 v6, 1
	s_movk_i32 s3, 0xb00
	v_lshlrev_b32_e32 v3, 5, v3
	v_ashrrev_i16_sdwa v4, v6, sext(v4) dst_sel:DWORD dst_unused:UNUSED_PAD src0_sel:DWORD src1_sel:BYTE_0
	v_mul_lo_u32 v5, v5, s3
	v_bfe_i32 v4, v4, 0, 16
	v_and_or_b32 v3, v3, 32, v5
	v_add_u32_e32 v2, 0x2000, v2
	v_add_lshl_u32 v130, v3, v4, 1
	v_ashrrev_i32_e32 v3, 31, v2
	v_lshrrev_b32_e32 v3, 22, v3
	v_add_u32_e32 v3, v2, v3
	v_ashrrev_i32_e32 v3, 10, v3
	v_mul_i32_i24_e32 v4, 0x400, v3
	v_sub_u32_e32 v2, v2, v4
	v_lshrrev_b32_e32 v4, 4, v2
	v_bitop3_b32 v2, v4, v2, 32 bitop3:0x6c
	v_ashrrev_i32_e32 v5, 31, v2
	v_lshrrev_b32_e32 v5, 26, v5
	s_add_u32 s8, s16, 0x2000000
	v_lshlrev_b32_e32 v4, 3, v3
	v_add_u32_e32 v5, v2, v5
	s_addc_u32 s2, s17, 0
	s_ashr_i32 s19, s27, 6
	v_and_b32_e32 v4, 0xfffff0, v4
	v_lshrrev_b32_e32 v7, 6, v5
	v_and_b32_e32 v5, 0xc0, v5
	v_add_u32_e32 v4, v7, v4
	v_sub_u32_e32 v2, v2, v5
	s_and_b32 s9, s2, 0xffff
	s_lshl_b32 s2, s19, 10
	v_lshlrev_b32_e32 v3, 5, v3
	v_ashrrev_i16_sdwa v2, v6, sext(v2) dst_sel:DWORD dst_unused:UNUSED_PAD src0_sel:DWORD src1_sel:BYTE_0
	v_mul_lo_u32 v4, v4, s3
	s_add_i32 s28, s2, 0
	v_bfe_i32 v2, v2, 0, 16
	v_and_or_b32 v3, v3, 32, v4
	s_mov_b32 s11, 0x20000
	s_mov_b32 s10, -1
	s_mul_i32 s33, s18, 0x160000
	s_add_i32 s29, s28, 0x10000
	v_add_lshl_u32 v131, v3, v2, 1
	s_add_i32 s34, s28, 0x12000
	s_add_i32 s35, s28, 0x14000
	s_add_i32 s2, s33, 0xb0000
	s_add_i32 s36, s28, 0x16000
	s_cmp_lg_u64 s[56:57], 0
	s_cbranch_scc1 .Lw0s_GEMM6
	s_mov_b32 m0, s29
	s_nop 0
	buffer_load_dwordx4 v130, s[8:11], s33 offen lds
	s_nop 0
	s_mov_b32 m0, s34
	s_nop 0
	buffer_load_dwordx4 v131, s[8:11], s33 offen lds
	s_nop 0
	s_mov_b32 m0, s35
	s_nop 0
	buffer_load_dwordx4 v130, s[8:11], s2 offen lds
	s_nop 0
	s_mov_b32 m0, s36
	s_nop 0
	buffer_load_dwordx4 v131, s[8:11], s2 offen lds
	s_nop 0
.Lw0s_GEMM6:
	s_and_saveexec_b64 s[2:3], s[56:57]
	s_cbranch_execz .LBB0_452
	v_mov_b32_e32 v2, 0
	global_load_dword v3, v2, s[0:1] sc1
	s_waitcnt vmcnt(0)
	v_cmp_lt_u32_e32 vcc, 23, v3
	s_cbranch_vccnz .LBB0_451
	s_mov_b32 s14, 1
	s_branch .LBB0_443

.LBB0_452:
	s_or_b64 exec, exec, s[2:3]
	s_add_u32 s12, s16, 0x5000000
	s_addc_u32 s0, s17, 0
	s_mul_i32 s3, s31, 0x160000
	s_and_b32 s13, s0, 0xffff
	s_mov_b32 s15, 0x20000
	s_mov_b32 s14, -1
	s_barrier
	s_cmp_eq_u64 s[56:57], 0
	s_cbranch_scc1 .Lw0n_GEMM6
	s_add_i32 s32, s33, 0xb0000
	s_mov_b32 m0, s29
	s_nop 0
	buffer_load_dwordx4 v130, s[8:11], s33 offen lds
	s_nop 0
	s_mov_b32 m0, s34
	s_nop 0
	buffer_load_dwordx4 v131, s[8:11], s33 offen lds
	s_nop 0
	s_mov_b32 m0, s35
	s_nop 0
	buffer_load_dwordx4 v130, s[8:11], s32 offen lds
	s_nop 0
	s_mov_b32 m0, s36
	s_nop 0
	buffer_load_dwordx4 v131, s[8:11], s32 offen lds
	s_nop 0
.Lw0n_GEMM6:
	s_mov_b32 m0, s28
	s_nop 0
	buffer_load_dwordx4 v130, s[12:15], s3 offen lds
	s_add_i32 s37, s28, 0x2000
	s_mov_b32 m0, s37
	s_nop 0
	buffer_load_dwordx4 v131, s[12:15], s3 offen lds
	s_add_i32 s38, s28, 0x4000
	s_add_i32 s0, s3, 0xb0000
	s_mov_b32 m0, s38
	s_nop 0
	buffer_load_dwordx4 v130, s[12:15], s0 offen lds
	s_add_i32 s39, s28, 0x6000
	s_mov_b32 m0, s39
	s_nop 0
	buffer_load_dwordx4 v131, s[12:15], s0 offen lds
	s_ashr_i32 s24, s27, 8
	s_cmp_lg_u32 s24, 1
	s_cbranch_scc1 .LBB0_454
	s_barrier

.LBB0_590:
	s_and_b64 vcc, exec, s[4:5]
	s_cbranch_vccz .LBB0_605
	v_ashrrev_i32_e32 v3, 31, v2
	v_lshrrev_b32_e32 v3, 26, v3
	v_add_u32_e32 v3, v2, v3
	v_ashrrev_i32_e32 v4, 6, v3
	v_bfe_i32 v3, v2, 27, 1
	v_lshlrev_b32_e32 v5, 4, v2
	v_lshrrev_b32_e32 v3, 22, v3
	v_add_u32_e32 v3, v5, v3
	v_and_b32_e32 v3, 0xfffffc00, v3
	v_sub_u32_e32 v3, v5, v3
	v_lshrrev_b32_e32 v6, 4, v3
	v_bitop3_b32 v6, v6, v3, 32 bitop3:0x6c
	v_ashrrev_i32_e32 v7, 31, v6
	v_lshrrev_b32_e32 v7, 26, v7
	v_add_u32_e32 v7, v6, v7
	v_ashrrev_i32_e32 v8, 6, v7
	v_and_b32_e32 v7, 0xc0, v7
	v_sub_u32_e32 v6, v6, v7
	v_mov_b32_e32 v7, 1
	v_lshlrev_b32_e32 v3, 3, v4
	v_lshlrev_b32_e32 v4, 5, v4
	v_ashrrev_i16_sdwa v6, v7, sext(v6) dst_sel:DWORD dst_unused:UNUSED_PAD src0_sel:DWORD src1_sel:BYTE_0
	v_and_b32_e32 v3, -16, v3
	v_and_b32_e32 v4, 32, v4
	v_bfe_i32 v6, v6, 0, 16
	v_add_u32_e32 v5, 0x2000, v5
	v_add_u32_e32 v3, v8, v3
	v_add_lshl_u32 v4, v4, v6, 1
	v_ashrrev_i32_e32 v6, 31, v5
	v_lshlrev_b32_e32 v9, 1, v3
	v_lshrrev_b32_e32 v10, 2, v3
	v_and_b32_e32 v8, 3, v8
	s_mov_b32 s5, 0x3fffe0
	v_lshrrev_b32_e32 v6, 22, v6
	v_and_b32_e32 v9, 24, v9
	v_and_b32_e32 v10, 4, v10
	v_and_or_b32 v8, v3, s5, v8
	v_add_u32_e32 v6, v5, v6
	v_or3_b32 v8, v8, v10, v9
	v_ashrrev_i32_e32 v6, 10, v6
	v_lshl_add_u32 v204, v8, 10, v4
	v_mul_i32_i24_e32 v8, 0x400, v6
	v_sub_u32_e32 v5, v5, v8
	v_lshrrev_b32_e32 v8, 4, v5
	v_bitop3_b32 v8, v8, v5, 32 bitop3:0x6c
	v_ashrrev_i32_e32 v9, 31, v8
	v_lshrrev_b32_e32 v9, 26, v9
	v_lshlrev_b32_e32 v5, 3, v6
	v_add_u32_e32 v9, v8, v9
	s_add_u32 s12, s20, 0x2b00000
	v_and_b32_e32 v5, -16, v5
	v_ashrrev_i32_e32 v10, 6, v9
	v_and_b32_e32 v9, 0xc0, v9
	s_addc_u32 s4, s21, 0
	s_ashr_i32 s34, s36, 6
	v_add_u32_e32 v5, v10, v5
	v_sub_u32_e32 v8, v8, v9
	v_lshlrev_b32_e32 v6, 5, v6
	v_ashrrev_i16_sdwa v7, v7, sext(v8) dst_sel:DWORD dst_unused:UNUSED_PAD src0_sel:DWORD src1_sel:BYTE_0
	v_lshlrev_b32_e32 v8, 1, v5
	v_lshrrev_b32_e32 v9, 2, v5
	v_and_b32_e32 v10, 3, v10
	s_and_b32 s13, s4, 0xffff
	s_lshl_b32 s4, s34, 10
	v_and_b32_e32 v6, 32, v6
	v_bfe_i32 v7, v7, 0, 16
	v_and_b32_e32 v8, 24, v8
	v_and_b32_e32 v9, 4, v9
	v_and_or_b32 v10, v5, s5, v10
	s_add_i32 s47, s4, 0
	v_or3_b32 v8, v10, v9, v8
	v_add_lshl_u32 v6, v6, v7, 1
	s_mov_b32 s15, 0x20000
	s_mov_b32 s14, -1
	s_lshl_b32 s41, s33, 18
	s_add_i32 s48, s47, 0x10000
	v_lshl_add_u32 v205, v8, 10, v6
	s_add_i32 s49, s47, 0x12000
	s_add_i32 s50, s47, 0x14000
	s_or_b32 s4, s41, 0x20000
	s_add_i32 s51, s47, 0x16000
	s_cmp_lg_u64 s[56:57], 0
	s_cbranch_scc1 .Lw0s_GEMM8
	s_mov_b32 m0, s48
	s_nop 0
	buffer_load_dwordx4 v204, s[12:15], s41 offen lds
	s_nop 0
	s_mov_b32 m0, s49
	s_nop 0
	buffer_load_dwordx4 v205, s[12:15], s41 offen lds
	s_nop 0
	s_mov_b32 m0, s50
	s_nop 0
	buffer_load_dwordx4 v204, s[12:15], s4 offen lds
	s_nop 0
	s_mov_b32 m0, s51
	s_nop 0
	buffer_load_dwordx4 v205, s[12:15], s4 offen lds
	s_nop 0
.Lw0s_GEMM8:
	s_and_saveexec_b64 s[4:5], s[56:57]
	s_cbranch_execz .LBB0_609
	v_mov_b32_e32 v7, 0
	global_load_dword v8, v7, s[2:3] sc1
	s_waitcnt vmcnt(0)
	v_cmp_lt_u32_e32 vcc, 31, v8
	s_cbranch_vccnz .LBB0_608
	s_mov_b32 s16, 1
	s_branch .LBB0_595

.LBB0_609:
	s_or_b64 exec, exec, s[4:5]
	s_add_u32 s16, s20, 0x5000000
	s_addc_u32 s1, s21, 0
	s_mul_i32 s2, s40, 0x160000
	v_lshl_add_u32 v206, v3, 10, v4
	s_and_b32 s17, s1, 0xffff
	s_mov_b32 s19, 0x20000
	s_mov_b32 s18, -1
	s_barrier
	s_cmp_eq_u64 s[56:57], 0
	s_cbranch_scc1 .Lw0n_GEMM8
	s_or_b32 s32, s41, 0x20000
	s_mov_b32 m0, s48
	s_nop 0
	buffer_load_dwordx4 v204, s[12:15], s41 offen lds
	s_nop 0
	s_mov_b32 m0, s49
	s_nop 0
	buffer_load_dwordx4 v205, s[12:15], s41 offen lds
	s_nop 0
	s_mov_b32 m0, s50
	s_nop 0
	buffer_load_dwordx4 v204, s[12:15], s32 offen lds
	s_nop 0
	s_mov_b32 m0, s51
	s_nop 0
	buffer_load_dwordx4 v205, s[12:15], s32 offen lds
	s_nop 0
.Lw0n_GEMM8:
	s_mov_b32 m0, s47
	s_nop 0
	buffer_load_dwordx4 v206, s[16:19], s2 offen lds
	v_lshl_add_u32 v207, v5, 10, v6
	s_add_i32 s52, s47, 0x2000
	s_mov_b32 m0, s52
	s_nop 0
	buffer_load_dwordx4 v207, s[16:19], s2 offen lds
	s_add_i32 s53, s47, 0x4000
	s_add_i32 s1, s2, 0x20000
	s_mov_b32 m0, s53
	s_nop 0
	buffer_load_dwordx4 v206, s[16:19], s1 offen lds
	s_ashr_i32 s0, s36, 8
	s_add_i32 s54, s47, 0x6000
	s_mov_b32 m0, s54
	s_nop 0
	buffer_load_dwordx4 v207, s[16:19], s1 offen lds
	s_cmp_eq_u32 s0, 1
	s_mov_b32 s80, s73
	s_mov_b32 s77, s72
	s_mov_b32 s11, 0
	s_cselect_b64 s[24:25], -1, 0
	s_cmp_lg_u32 s0, 1
	s_cbranch_scc1 .LBB0_611
	s_barrier

.LBB0_919:
	v_bfe_i32 v4, v241, 27, 1
	v_lshlrev_b32_e32 v2, 4, v241
	v_lshrrev_b32_e32 v4, 22, v4
	v_add_u32_e32 v4, v2, v4
	v_and_b32_e32 v4, 0xfffffc00, v4
	v_sub_u32_e32 v4, v2, v4
	v_lshrrev_b32_e32 v5, 4, v4
	v_bitop3_b32 v4, v5, v4, 32 bitop3:0x6c
	v_ashrrev_i32_e32 v3, 31, v241
	v_ashrrev_i32_e32 v6, 31, v4
	v_lshrrev_b32_e32 v3, 26, v3
	v_lshrrev_b32_e32 v6, 26, v6
	v_add_u32_e32 v3, v241, v3
	v_add_u32_e32 v6, v4, v6
	v_ashrrev_i32_e32 v3, 6, v3
	v_lshrrev_b32_e32 v7, 6, v6
	v_and_b32_e32 v6, 0xc0, v6
	v_lshlrev_b32_e32 v5, 3, v3
	v_lshlrev_b32_e32 v3, 5, v3
	v_sub_u32_e32 v4, v4, v6
	v_mov_b32_e32 v8, 1
	v_and_b32_e32 v5, 0x3ffff0, v5
	v_and_b32_e32 v3, 32, v3
	v_ashrrev_i16_sdwa v4, v8, sext(v4) dst_sel:DWORD dst_unused:UNUSED_PAD src0_sel:DWORD src1_sel:BYTE_0
	v_add_u32_sdwa v3, v3, sext(v4) dst_sel:DWORD dst_unused:UNUSED_PAD src0_sel:DWORD src1_sel:WORD_0
	v_add_lshl_u32 v4, v7, v5, 10
	v_add_u32_e32 v2, 0x2000, v2
	v_lshl_add_u32 v6, v3, 1, v4
	v_ashrrev_i32_e32 v3, 31, v2
	s_add_u32 s8, s16, 0x2e00000
	v_lshrrev_b32_e32 v3, 22, v3
	s_addc_u32 s3, s17, 0
	v_add_u32_e32 v3, v2, v3
	s_add_i32 s2, s4, s2
	v_ashrrev_i32_e32 v3, 10, v3
	s_ashr_i32 s4, s2, 31
	v_mul_i32_i24_e32 v4, 0x400, v3
	s_lshr_b32 s4, s4, 27
	v_sub_u32_e32 v2, v2, v4
	s_add_i32 s15, s2, s4
	v_lshrrev_b32_e32 v4, 4, v2
	s_and_b32 s4, s15, 0xffe0
	v_bitop3_b32 v2, v4, v2, 32 bitop3:0x6c
	s_sub_i32 s14, s2, s4
	v_ashrrev_i32_e32 v5, 31, v2
	s_bfe_i32 s2, s14, 0x80000
	v_lshrrev_b32_e32 v5, 26, v5
	s_bfe_u32 s2, s2, 0x3000c
	v_add_u32_e32 v5, v2, v5
	s_add_i32 s2, s14, s2
	s_ashr_i32 s19, s26, 6
	v_lshrrev_b32_e32 v7, 6, v5
	v_and_b32_e32 v5, 0xc0, v5
	s_bfe_i32 s2, s2, 0x80000
	v_lshlrev_b32_e32 v4, 3, v3
	v_lshlrev_b32_e32 v3, 5, v3
	v_sub_u32_e32 v2, v2, v5
	s_and_b32 s9, s3, 0xffff
	s_lshl_b32 s3, s19, 10
	s_sext_i32_i16 s30, s2
	v_and_b32_e32 v4, 0x3ffff0, v4
	v_and_b32_e32 v3, 32, v3
	v_ashrrev_i16_sdwa v2, v8, sext(v2) dst_sel:DWORD dst_unused:UNUSED_PAD src0_sel:DWORD src1_sel:BYTE_0
	s_ashr_i32 s18, s30, 3
	s_add_i32 s28, s3, 0
	v_add_u32_sdwa v2, v3, sext(v2) dst_sel:DWORD dst_unused:UNUSED_PAD src0_sel:DWORD src1_sel:WORD_0
	v_add_lshl_u32 v3, v7, v4, 10
	s_mov_b32 s11, 0x20000
	s_mov_b32 s10, -1
	s_lshl_b32 s33, s18, 18
	s_add_i32 s29, s28, 0x10000
	v_lshl_add_u32 v7, v2, 1, v3
	s_add_i32 s34, s28, 0x12000
	s_add_i32 s35, s28, 0x14000
	s_or_b32 s2, s33, 0x20000
	s_add_i32 s36, s28, 0x16000
	s_cmp_lg_u64 s[56:57], 0
	s_cbranch_scc1 .Lw0s_GEMM10
	s_mov_b32 m0, s29
	s_nop 0
	buffer_load_dwordx4 v6, s[8:11], s33 offen lds
	s_nop 0
	s_mov_b32 m0, s34
	s_nop 0
	buffer_load_dwordx4 v7, s[8:11], s33 offen lds
	s_nop 0
	s_mov_b32 m0, s35
	s_nop 0
	buffer_load_dwordx4 v6, s[8:11], s2 offen lds
	s_nop 0
	s_mov_b32 m0, s36
	s_nop 0
	buffer_load_dwordx4 v7, s[8:11], s2 offen lds
	s_nop 0
.Lw0s_GEMM10:
	s_and_saveexec_b64 s[2:3], s[56:57]
	s_cbranch_execz .LBB0_932
	v_mov_b32_e32 v2, 0
	global_load_dword v3, v2, s[0:1] sc1
	s_waitcnt vmcnt(0)
	v_cmp_lt_u32_e32 vcc, 39, v3
	s_cbranch_vccnz .LBB0_931
	s_mov_b32 s31, 1
	s_branch .LBB0_923

.LBB0_932:
	s_or_b64 exec, exec, s[2:3]
	s_lshr_b32 s1, s30, 3
	s_lshl_b32 s1, s1, 3
	s_ashr_i32 s0, s15, 5
	s_sub_i32 s1, s14, s1
	s_lshl_b32 s0, s0, 3
	s_sext_i32_i8 s1, s1
	s_add_i32 s31, s0, s1
	s_lshl_b32 s37, s31, 19
	s_add_u32 s12, s16, 0xdc00000
	s_addc_u32 s0, s17, 0
	s_and_b32 s13, s0, 0xffff
	s_mov_b32 s15, 0x20000
	s_mov_b32 s14, -1
	s_barrier
	s_cmp_eq_u64 s[56:57], 0
	s_cbranch_scc1 .Lw0n_GEMM10
	s_or_b32 s32, s33, 0x20000
	s_mov_b32 m0, s29
	s_nop 0
	buffer_load_dwordx4 v6, s[8:11], s33 offen lds
	s_nop 0
	s_mov_b32 m0, s34
	s_nop 0
	buffer_load_dwordx4 v7, s[8:11], s33 offen lds
	s_nop 0
	s_mov_b32 m0, s35
	s_nop 0
	buffer_load_dwordx4 v6, s[8:11], s32 offen lds
	s_nop 0
	s_mov_b32 m0, s36
	s_nop 0
	buffer_load_dwordx4 v7, s[8:11], s32 offen lds
	s_nop 0
.Lw0n_GEMM10:
	s_mov_b32 m0, s28
	s_nop 0
	buffer_load_dwordx4 v6, s[12:15], s37 offen lds
	s_add_i32 s38, s28, 0x2000
	s_mov_b32 m0, s38
	s_nop 0
	buffer_load_dwordx4 v7, s[12:15], s37 offen lds
	s_add_i32 s40, s28, 0x4000
	s_or_b32 s0, s37, 0x20000
	s_mov_b32 m0, s40
	s_nop 0
	buffer_load_dwordx4 v6, s[12:15], s0 offen lds
	s_add_i32 s41, s28, 0x6000
	s_mov_b32 m0, s41
	s_nop 0
	buffer_load_dwordx4 v7, s[12:15], s0 offen lds
	s_ashr_i32 s2, s26, 8
	s_mov_b32 s39, 0
	s_cmp_lg_u32 s2, 1
	s_cbranch_scc1 .LBB0_934
	s_barrier

.LBB0_1050:
	s_and_b64 vcc, exec, s[6:7]
	s_cbranch_vccz .LBB0_1079
	v_ashrrev_i32_e32 v3, 31, v2
	v_lshrrev_b32_e32 v3, 26, v3
	v_add_u32_e32 v3, v2, v3
	v_ashrrev_i32_e32 v4, 6, v3
	v_bfe_i32 v3, v2, 27, 1
	v_lshlrev_b32_e32 v5, 4, v2
	v_lshrrev_b32_e32 v3, 22, v3
	v_add_u32_e32 v3, v5, v3
	v_and_b32_e32 v3, 0xfffffc00, v3
	v_sub_u32_e32 v3, v5, v3
	v_lshrrev_b32_e32 v6, 4, v3
	v_bitop3_b32 v6, v6, v3, 32 bitop3:0x6c
	v_ashrrev_i32_e32 v7, 31, v6
	v_lshrrev_b32_e32 v7, 26, v7
	v_add_u32_e32 v7, v6, v7
	v_ashrrev_i32_e32 v8, 6, v7
	v_and_b32_e32 v7, 0xc0, v7
	v_sub_u32_e32 v6, v6, v7
	v_mov_b32_e32 v7, 1
	v_lshlrev_b32_e32 v3, 3, v4
	v_lshlrev_b32_e32 v4, 5, v4
	v_ashrrev_i16_sdwa v6, v7, sext(v6) dst_sel:DWORD dst_unused:UNUSED_PAD src0_sel:DWORD src1_sel:BYTE_0
	v_and_b32_e32 v3, -16, v3
	v_and_b32_e32 v4, 32, v4
	v_bfe_i32 v6, v6, 0, 16
	v_add_u32_e32 v5, 0x2000, v5
	v_add_u32_e32 v3, v8, v3
	v_add_lshl_u32 v4, v4, v6, 1
	v_ashrrev_i32_e32 v6, 31, v5
	v_lshlrev_b32_e32 v9, 1, v3
	v_lshrrev_b32_e32 v10, 2, v3
	v_and_b32_e32 v8, 3, v8
	s_mov_b32 s7, 0x3fffe0
	v_lshrrev_b32_e32 v6, 22, v6
	v_and_b32_e32 v9, 24, v9
	v_and_b32_e32 v10, 4, v10
	v_and_or_b32 v8, v3, s7, v8
	v_add_u32_e32 v6, v5, v6
	v_or3_b32 v8, v8, v10, v9
	v_ashrrev_i32_e32 v6, 10, v6
	v_lshl_add_u32 v144, v8, 10, v4
	v_mul_i32_i24_e32 v8, 0x400, v6
	v_sub_u32_e32 v5, v5, v8
	v_lshrrev_b32_e32 v8, 4, v5
	v_bitop3_b32 v8, v8, v5, 32 bitop3:0x6c
	v_ashrrev_i32_e32 v9, 31, v8
	v_lshrrev_b32_e32 v9, 26, v9
	v_lshlrev_b32_e32 v5, 3, v6
	v_add_u32_e32 v9, v8, v9
	s_add_u32 s8, s0, 0x1500000
	v_and_b32_e32 v5, -16, v5
	v_ashrrev_i32_e32 v10, 6, v9
	s_addc_u32 s6, s1, 0
	v_add_u32_e32 v5, v10, v5
	v_and_b32_e32 v10, 3, v10
	s_ashr_i32 s25, s24, 31
	v_and_or_b32 v10, v5, s7, v10
	s_lshr_b32 s7, s25, 29
	s_add_i32 s7, s24, s7
	s_ashr_i32 s21, s20, 6
	s_ashr_i32 s12, s7, 3
	s_and_b32 s7, s7, -8
	s_and_b32 s9, s6, 0xffff
	s_lshl_b32 s6, s21, 10
	s_sub_i32 s7, s24, s7
	s_cmp_lt_i32 s7, 0
	s_movk_i32 s13, 0xb1
	s_cselect_b32 s13, s13, 0xb0
	s_mul_i32 s7, s7, s13
	s_add_i32 s7, s7, s12
	s_mul_hi_i32 s12, s7, 0x2e8ba2e9
	s_lshr_b32 s13, s12, 31
	s_ashr_i32 s18, s12, 5
	s_add_i32 s18, s18, s13
	s_mul_i32 s12, s18, 0xb0
	s_sub_i32 s19, s7, s12
	v_and_b32_e32 v9, 0xc0, v9
	s_bfe_u32 s7, s19, 0x3001c
	v_sub_u32_e32 v8, v8, v9
	s_add_i32 s7, s19, s7
	v_lshlrev_b32_e32 v6, 5, v6
	v_ashrrev_i16_sdwa v7, v7, sext(v8) dst_sel:DWORD dst_unused:UNUSED_PAD src0_sel:DWORD src1_sel:BYTE_0
	v_lshlrev_b32_e32 v8, 1, v5
	v_lshrrev_b32_e32 v9, 2, v5
	s_sext_i32_i16 s22, s7
	v_and_b32_e32 v6, 32, v6
	v_bfe_i32 v7, v7, 0, 16
	v_and_b32_e32 v8, 24, v8
	v_and_b32_e32 v9, 4, v9
	s_ashr_i32 s52, s22, 3
	s_add_i32 s26, s6, 0
	v_or3_b32 v8, v10, v9, v8
	v_add_lshl_u32 v6, v6, v7, 1
	s_mov_b32 s11, 0x20000
	s_mov_b32 s10, -1
	s_lshl_b32 s58, s52, 18
	s_add_i32 s27, s26, 0x10000
	v_lshl_add_u32 v145, v8, 10, v6
	s_add_i32 s28, s26, 0x12000
	s_add_i32 s29, s26, 0x14000
	s_or_b32 s6, s58, 0x20000
	s_add_i32 s30, s26, 0x16000
	s_cmp_lg_u64 s[56:57], 0
	s_cbranch_scc1 .Lw0s_GEMM12
	s_mov_b32 m0, s27
	s_nop 0
	buffer_load_dwordx4 v144, s[8:11], s58 offen lds
	s_nop 0
	s_mov_b32 m0, s28
	s_nop 0
	buffer_load_dwordx4 v145, s[8:11], s58 offen lds
	s_nop 0
	s_mov_b32 m0, s29
	s_nop 0
	buffer_load_dwordx4 v144, s[8:11], s6 offen lds
	s_nop 0
	s_mov_b32 m0, s30
	s_nop 0
	buffer_load_dwordx4 v145, s[8:11], s6 offen lds
	s_nop 0
.Lw0s_GEMM12:
	s_and_saveexec_b64 s[6:7], s[56:57]
	s_cbranch_execz .LBB0_1064
	v_mov_b32_e32 v7, 0
	global_load_dword v8, v7, s[4:5] sc1
	s_waitcnt vmcnt(0)
	v_cmp_lt_u32_e32 vcc, 47, v8
	s_cbranch_vccnz .LBB0_1063
	s_mov_b32 s31, 1
	s_branch .LBB0_1055

.LBB0_1064:
	s_or_b64 exec, exec, s[6:7]
	s_lshr_b32 s2, s22, 3
	s_lshl_b32 s2, s2, 3
	s_sub_i32 s2, s19, s2
	s_lshl_b32 s3, s18, 3
	s_sext_i32_i16 s2, s2
	s_add_i32 s53, s3, s2
	s_lshl_b32 s55, s53, 19
	s_add_u32 s12, s0, 0xa800000
	s_addc_u32 s2, s1, 0
	v_lshl_add_u32 v146, v3, 10, v4
	s_and_b32 s13, s2, 0xffff
	s_mov_b32 s15, 0x20000
	s_mov_b32 s14, -1
	s_barrier
	s_cmp_eq_u64 s[56:57], 0
	s_cbranch_scc1 .Lw0n_GEMM12
	s_or_b32 s32, s58, 0x20000
	s_mov_b32 m0, s27
	s_nop 0
	buffer_load_dwordx4 v144, s[8:11], s58 offen lds
	s_nop 0
	s_mov_b32 m0, s28
	s_nop 0
	buffer_load_dwordx4 v145, s[8:11], s58 offen lds
	s_nop 0
	s_mov_b32 m0, s29
	s_nop 0
	buffer_load_dwordx4 v144, s[8:11], s32 offen lds
	s_nop 0
	s_mov_b32 m0, s30
	s_nop 0
	buffer_load_dwordx4 v145, s[8:11], s32 offen lds
	s_nop 0
.Lw0n_GEMM12:
	s_mov_b32 m0, s26
	s_nop 0
	buffer_load_dwordx4 v146, s[12:15], s55 offen lds
	v_lshl_add_u32 v147, v5, 10, v6
	s_add_i32 s2, s26, 0x2000
	s_mov_b32 m0, s2
	s_nop 0
	buffer_load_dwordx4 v147, s[12:15], s55 offen lds
	s_add_i32 s3, s26, 0x4000
	s_or_b32 s5, s55, 0x20000
	s_mov_b32 m0, s3
	s_nop 0
	buffer_load_dwordx4 v146, s[12:15], s5 offen lds
	s_ashr_i32 s4, s20, 8
	s_add_i32 s31, s26, 0x6000
	s_mov_b32 m0, s31
	s_nop 0
	buffer_load_dwordx4 v147, s[12:15], s5 offen lds
	s_cmp_eq_u32 s4, 1
	s_mov_b32 s50, 0
	s_cselect_b64 s[6:7], -1, 0
	s_cmp_lg_u32 s4, 1
	s_cbranch_scc1 .LBB0_1066
	s_barrier

.LBB0_1101:
	s_and_b64 vcc, exec, s[2:3]
	s_cbranch_vccz .LBB0_1116
	v_bfe_i32 v4, v0, 27, 1
	v_lshlrev_b32_e32 v2, 4, v0
	v_lshrrev_b32_e32 v4, 22, v4
	v_add_u32_e32 v4, v2, v4
	v_and_b32_e32 v4, 0xfffffc00, v4
	v_sub_u32_e32 v4, v2, v4
	v_ashrrev_i32_e32 v3, 31, v0
	v_lshrrev_b32_e32 v5, 4, v4
	v_lshrrev_b32_e32 v3, 26, v3
	v_bitop3_b32 v4, v5, v4, 32 bitop3:0x6c
	v_add_u32_e32 v3, v0, v3
	v_ashrrev_i32_e32 v6, 31, v4
	v_ashrrev_i32_e32 v3, 6, v3
	v_lshrrev_b32_e32 v6, 26, v6
	v_lshlrev_b32_e32 v5, 3, v3
	v_add_u32_e32 v6, v4, v6
	v_and_b32_e32 v5, 0xfffff0, v5
	v_lshrrev_b32_e32 v7, 6, v6
	v_and_b32_e32 v6, 0xc0, v6
	v_add_u32_e32 v5, v7, v5
	v_sub_u32_e32 v4, v4, v6
	v_mov_b32_e32 v6, 1
	s_movk_i32 s3, 0xb00
	v_lshlrev_b32_e32 v3, 5, v3
	v_ashrrev_i16_sdwa v4, v6, sext(v4) dst_sel:DWORD dst_unused:UNUSED_PAD src0_sel:DWORD src1_sel:BYTE_0
	v_mul_lo_u32 v5, v5, s3
	v_bfe_i32 v4, v4, 0, 16
	v_and_or_b32 v3, v3, 32, v5
	v_add_u32_e32 v2, 0x2000, v2
	v_add_lshl_u32 v134, v3, v4, 1
	v_ashrrev_i32_e32 v3, 31, v2
	v_lshrrev_b32_e32 v3, 22, v3
	v_add_u32_e32 v3, v2, v3
	v_ashrrev_i32_e32 v3, 10, v3
	v_mul_i32_i24_e32 v4, 0x400, v3
	v_sub_u32_e32 v2, v2, v4
	v_lshrrev_b32_e32 v4, 4, v2
	v_bitop3_b32 v2, v4, v2, 32 bitop3:0x6c
	v_ashrrev_i32_e32 v5, 31, v2
	v_lshrrev_b32_e32 v5, 26, v5
	s_add_u32 s12, s10, 0x2580000
	v_lshlrev_b32_e32 v4, 3, v3
	v_add_u32_e32 v5, v2, v5
	s_addc_u32 s2, s11, 0
	s_ashr_i32 s21, s27, 6
	v_and_b32_e32 v4, 0xfffff0, v4
	v_lshrrev_b32_e32 v7, 6, v5
	v_and_b32_e32 v5, 0xc0, v5
	v_add_u32_e32 v4, v7, v4
	v_sub_u32_e32 v2, v2, v5
	s_and_b32 s13, s2, 0xffff
	s_lshl_b32 s2, s21, 10
	v_lshlrev_b32_e32 v3, 5, v3
	v_ashrrev_i16_sdwa v2, v6, sext(v2) dst_sel:DWORD dst_unused:UNUSED_PAD src0_sel:DWORD src1_sel:BYTE_0
	v_mul_lo_u32 v4, v4, s3
	s_add_i32 s28, s2, 0
	v_bfe_i32 v2, v2, 0, 16
	v_and_or_b32 v3, v3, 32, v4
	s_mov_b32 s15, 0x20000
	s_mov_b32 s14, -1
	s_mul_i32 s30, s20, 0x160000
	s_add_i32 s29, s28, 0x10000
	v_add_lshl_u32 v135, v3, v2, 1
	s_add_i32 s33, s28, 0x12000
	s_add_i32 s34, s28, 0x14000
	s_add_i32 s2, s30, 0xb0000
	s_add_i32 s35, s28, 0x16000
	s_cmp_lg_u64 s[56:57], 0
	s_cbranch_scc1 .Lw0s_GEMM13
	s_mov_b32 m0, s29
	s_nop 0
	buffer_load_dwordx4 v134, s[12:15], s30 offen lds
	s_nop 0
	s_mov_b32 m0, s33
	s_nop 0
	buffer_load_dwordx4 v135, s[12:15], s30 offen lds
	s_nop 0
	s_mov_b32 m0, s34
	s_nop 0
	buffer_load_dwordx4 v134, s[12:15], s2 offen lds
	s_nop 0
	s_mov_b32 m0, s35
	s_nop 0
	buffer_load_dwordx4 v135, s[12:15], s2 offen lds
	s_nop 0
.Lw0s_GEMM13:
	s_and_saveexec_b64 s[2:3], s[56:57]
	s_cbranch_execz .LBB0_1120
	v_mov_b32_e32 v2, 0
	global_load_dword v3, v2, s[0:1] sc1
	s_waitcnt vmcnt(0)
	v_cmp_lt_u32_e32 vcc, 51, v3
	s_cbranch_vccnz .LBB0_1119
	s_mov_b32 s24, 1
	s_branch .LBB0_1106

.LBB0_1120:
	s_or_b64 exec, exec, s[2:3]
	s_add_u32 s16, s10, 0x5000000
	s_addc_u32 s0, s11, 0
	s_mul_i32 s36, s25, 0x160000
	s_and_b32 s17, s0, 0xffff
	s_mov_b32 s19, 0x20000
	s_mov_b32 s18, -1
	s_waitcnt lgkmcnt(0)
	s_barrier
	s_cmp_eq_u64 s[56:57], 0
	s_cbranch_scc1 .Lw0n_GEMM13
	s_add_i32 s32, s30, 0xb0000
	s_mov_b32 m0, s29
	s_nop 0
	buffer_load_dwordx4 v134, s[12:15], s30 offen lds
	s_nop 0
	s_mov_b32 m0, s33
	s_nop 0
	buffer_load_dwordx4 v135, s[12:15], s30 offen lds
	s_nop 0
	s_mov_b32 m0, s34
	s_nop 0
	buffer_load_dwordx4 v134, s[12:15], s32 offen lds
	s_nop 0
	s_mov_b32 m0, s35
	s_nop 0
	buffer_load_dwordx4 v135, s[12:15], s32 offen lds
	s_nop 0
.Lw0n_GEMM13:
	s_mov_b32 m0, s28
	s_nop 0
	buffer_load_dwordx4 v134, s[16:19], s36 offen lds
	s_add_i32 s37, s28, 0x2000
	s_mov_b32 m0, s37
	s_nop 0
	buffer_load_dwordx4 v135, s[16:19], s36 offen lds
	s_add_i32 s38, s28, 0x4000
	s_add_i32 s0, s36, 0xb0000
	s_mov_b32 m0, s38
	s_nop 0
	buffer_load_dwordx4 v134, s[16:19], s0 offen lds
	s_add_i32 s39, s28, 0x6000
	s_mov_b32 m0, s39
	s_nop 0
	buffer_load_dwordx4 v135, s[16:19], s0 offen lds
	s_ashr_i32 s26, s27, 8
	s_cmp_lg_u32 s26, 1
	s_cbranch_scc1 .LBB0_1122
	s_barrier
